# attention: window tiles whose keys are all valid for the wave take the unmasked softmax path
# baseline (speedup 1.0000x reference)
.LBB0_379:
	v_add_u32_e32 v122, v108, v110
	ds_read_b128 v[32:35], v122
	ds_read_b128 v[36:39], v122 offset:32
	v_add_u32_e32 v127, s95, v97
	v_cmp_gt_u32_e32 vcc, s9, v127
	s_waitcnt lgkmcnt(1)
	v_mfma_f32_32x32x16_bf16 v[48:63], v[32:35], v[72:75], 0
	ds_read_b128 v[32:35], v122 offset:64
	ds_read_b128 v[118:121], v122 offset:4640
	s_waitcnt lgkmcnt(2)
	v_mfma_f32_32x32x16_bf16 v[48:63], v[36:39], v[76:79], v[48:63]
	s_waitcnt lgkmcnt(1)
	v_mfma_f32_32x32x16_bf16 v[48:63], v[32:35], v[84:87], v[48:63]
	ds_read_b128 v[32:35], v122 offset:96
	s_waitcnt lgkmcnt(0)
	v_mfma_f32_32x32x16_bf16 v[48:63], v[32:35], v[92:95], v[48:63]
	ds_read_b128 v[32:35], v122 offset:4608
	s_waitcnt lgkmcnt(0)
	v_mfma_f32_32x32x16_bf16 v[32:47], v[32:35], v[72:75], 0
	v_mfma_f32_32x32x16_bf16 v[32:47], v[118:121], v[76:79], v[32:47]
	ds_read_b128 v[118:121], v122 offset:4672
	s_waitcnt lgkmcnt(0)
	v_mfma_f32_32x32x16_bf16 v[32:47], v[118:121], v[84:87], v[32:47]
	ds_read_b128 v[118:121], v122 offset:4704
	s_waitcnt lgkmcnt(0)
	v_mfma_f32_32x32x16_bf16 v[32:47], v[118:121], v[92:95], v[32:47]
	ds_read_b64_tr_b16 v[134:135], v167 offset:9216
	ds_read_b64_tr_b16 v[136:137], v167 offset:10368
	ds_read_b64_tr_b16 v[138:139], v167 offset:9792
	ds_read_b64_tr_b16 v[140:141], v167 offset:10944
	ds_read_b64_tr_b16 v[142:143], v167 offset:11520
	ds_read_b64_tr_b16 v[144:145], v167 offset:12672
	ds_read_b64_tr_b16 v[146:147], v167 offset:12096
	ds_read_b64_tr_b16 v[148:149], v167 offset:13248
	ds_read_b64_tr_b16 v[150:151], v167 offset:13824
	ds_read_b64_tr_b16 v[152:153], v167 offset:14976
	ds_read_b64_tr_b16 v[154:155], v167 offset:14400
	ds_read_b64_tr_b16 v[156:157], v167 offset:15552
	ds_read_b64_tr_b16 v[158:159], v167 offset:16128
	ds_read_b64_tr_b16 v[160:161], v167 offset:17280
	ds_read_b64_tr_b16 v[162:163], v167 offset:16704
	ds_read_b64_tr_b16 v[164:165], v167 offset:17856
	v_add_u32_e32 v173, 59, v127
	v_cmp_gt_u32_e64 s[98:99], s9, v173
	s_nop 1
	s_and_b64 s[98:99], s[98:99], vcc
	s_cmp_eq_u64 s[98:99], -1
	s_cbranch_scc1 .Lattn_nomask
	s_cmp_eq_u64 s[64:65], 0
	s_cbranch_scc1 .Lattn_nomask
	s_nop 1
	v_cndmask_b32_e32 v118, v189, v48, vcc
	v_cndmask_b32_e64 v48, v48, v118, s[64:65]
	v_add_u32_e32 v118, 1, v127
	v_cmp_gt_u32_e32 vcc, s9, v118
	s_nop 1
	v_cndmask_b32_e32 v118, v189, v49, vcc
	v_cndmask_b32_e64 v49, v49, v118, s[64:65]
	v_add_u32_e32 v118, 2, v127
	v_cmp_gt_u32_e32 vcc, s9, v118
	v_max3_f32 v119, v117, v48, v49
	s_nop 0
	v_cndmask_b32_e32 v118, v189, v50, vcc
	v_cndmask_b32_e64 v50, v50, v118, s[64:65]
	v_add_u32_e32 v118, 3, v127
	v_cmp_gt_u32_e32 vcc, s9, v118
	s_nop 1
	v_cndmask_b32_e32 v118, v189, v51, vcc
	v_cndmask_b32_e64 v118, v51, v118, s[64:65]
	v_max3_f32 v51, v119, v50, v118
	v_add_u32_e32 v119, 8, v127
	v_cmp_gt_u32_e32 vcc, s9, v119
	s_nop 1
	v_cndmask_b32_e32 v119, v189, v52, vcc
	v_cndmask_b32_e64 v52, v52, v119, s[64:65]
	v_add_u32_e32 v119, 9, v127
	v_cmp_gt_u32_e32 vcc, s9, v119
	s_nop 1
	v_cndmask_b32_e32 v119, v189, v53, vcc
	v_cndmask_b32_e64 v53, v53, v119, s[64:65]
	v_add_u32_e32 v119, 10, v127
	v_cmp_gt_u32_e32 vcc, s9, v119
	v_max3_f32 v51, v51, v52, v53
	s_nop 0
	v_cndmask_b32_e32 v119, v189, v54, vcc
	v_cndmask_b32_e64 v54, v54, v119, s[64:65]
	v_add_u32_e32 v119, 11, v127
	v_cmp_gt_u32_e32 vcc, s9, v119
	s_nop 1
	v_cndmask_b32_e32 v119, v189, v55, vcc
	v_cndmask_b32_e64 v119, v55, v119, s[64:65]
	v_add_u32_e32 v55, 16, v127
	v_cmp_gt_u32_e32 vcc, s9, v55
	v_max3_f32 v51, v51, v54, v119
	s_nop 0
	v_cndmask_b32_e32 v55, v189, v56, vcc
	v_cndmask_b32_e64 v121, v56, v55, s[64:65]
	v_add_u32_e32 v55, 17, v127
	v_cmp_gt_u32_e32 vcc, s9, v55
	s_nop 1
	v_cndmask_b32_e32 v55, v189, v57, vcc
	v_cndmask_b32_e64 v120, v57, v55, s[64:65]
	v_add_u32_e32 v55, 18, v127
	v_cmp_gt_u32_e32 vcc, s9, v55
	v_max3_f32 v51, v51, v121, v120
	s_nop 0
	v_cndmask_b32_e32 v55, v189, v58, vcc
	v_cndmask_b32_e64 v122, v58, v55, s[64:65]
	v_add_u32_e32 v55, 19, v127
	v_cmp_gt_u32_e32 vcc, s9, v55
	s_nop 1
	v_cndmask_b32_e32 v55, v189, v59, vcc
	v_cndmask_b32_e64 v123, v59, v55, s[64:65]
	v_add_u32_e32 v55, 24, v127
	v_cmp_gt_u32_e32 vcc, s9, v55
	v_max3_f32 v51, v51, v122, v123
	s_nop 0
	v_cndmask_b32_e32 v55, v189, v60, vcc
	v_cndmask_b32_e64 v60, v60, v55, s[64:65]
	v_add_u32_e32 v55, 25, v127
	v_cmp_gt_u32_e32 vcc, s9, v55
	s_nop 1
	v_cndmask_b32_e32 v55, v189, v61, vcc
	v_cndmask_b32_e64 v61, v61, v55, s[64:65]
	v_add_u32_e32 v55, 26, v127
	v_cmp_gt_u32_e32 vcc, s9, v55
	v_max3_f32 v51, v51, v60, v61
	s_nop 0
	v_cndmask_b32_e32 v55, v189, v62, vcc
	v_cndmask_b32_e64 v62, v62, v55, s[64:65]
	v_add_u32_e32 v55, 27, v127
	v_cmp_gt_u32_e32 vcc, s9, v55
	s_nop 1
	v_cndmask_b32_e32 v55, v189, v63, vcc
	v_cndmask_b32_e64 v63, v63, v55, s[64:65]
	v_add_u32_e32 v55, 32, v127
	v_cmp_gt_u32_e32 vcc, s9, v55
	v_max3_f32 v51, v51, v62, v63
	s_nop 0
	v_cndmask_b32_e32 v55, v189, v32, vcc
	v_cndmask_b32_e64 v124, v32, v55, s[64:65]
	v_add_u32_e32 v32, 33, v127
	v_cmp_gt_u32_e32 vcc, s9, v32
	s_nop 1
	v_cndmask_b32_e32 v32, v189, v33, vcc
	v_cndmask_b32_e64 v125, v33, v32, s[64:65]
	v_add_u32_e32 v33, 34, v127
	v_cmp_gt_u32_e32 vcc, s9, v33
	v_max3_f32 v32, v51, v124, v125
	s_nop 0
	v_cndmask_b32_e32 v33, v189, v34, vcc
	v_cndmask_b32_e64 v126, v34, v33, s[64:65]
	v_add_u32_e32 v33, 35, v127
	v_cmp_gt_u32_e32 vcc, s9, v33
	v_add_u32_e32 v34, 57, v127
	s_nop 0
	v_cndmask_b32_e32 v33, v189, v35, vcc
	v_cndmask_b32_e64 v59, v35, v33, s[64:65]
	v_add_u32_e32 v33, 40, v127
	v_cmp_gt_u32_e32 vcc, s9, v33
	v_max3_f32 v32, v32, v126, v59
	s_nop 0
	v_cndmask_b32_e32 v33, v189, v36, vcc
	v_cndmask_b32_e64 v56, v36, v33, s[64:65]
	v_add_u32_e32 v33, 41, v127
	v_cmp_gt_u32_e32 vcc, s9, v33
	s_nop 1
	v_cndmask_b32_e32 v33, v189, v37, vcc
	v_cndmask_b32_e64 v57, v37, v33, s[64:65]
	v_add_u32_e32 v33, 42, v127
	v_cmp_gt_u32_e32 vcc, s9, v33
	v_max3_f32 v32, v32, v56, v57
	s_nop 0
	v_cndmask_b32_e32 v33, v189, v38, vcc
	v_cndmask_b32_e64 v58, v38, v33, s[64:65]
	v_add_u32_e32 v33, 43, v127
	v_cmp_gt_u32_e32 vcc, s9, v33
	s_nop 1
	v_cndmask_b32_e32 v33, v189, v39, vcc
	v_cndmask_b32_e64 v55, v39, v33, s[64:65]
	v_add_u32_e32 v33, 48, v127
	v_cmp_gt_u32_e32 vcc, s9, v33
	v_max3_f32 v32, v32, v58, v55
	s_nop 0
	v_cndmask_b32_e32 v33, v189, v40, vcc
	v_cndmask_b32_e64 v37, v40, v33, s[64:65]
	v_add_u32_e32 v33, 49, v127
	v_cmp_gt_u32_e32 vcc, s9, v33
	s_nop 1
	v_cndmask_b32_e32 v33, v189, v41, vcc
	v_cndmask_b32_e64 v38, v41, v33, s[64:65]
	v_add_u32_e32 v33, 50, v127
	v_cmp_gt_u32_e32 vcc, s9, v33
	v_max3_f32 v32, v32, v37, v38
	s_nop 0
	v_cndmask_b32_e32 v33, v189, v42, vcc
	v_cndmask_b32_e64 v39, v42, v33, s[64:65]
	v_add_u32_e32 v33, 51, v127
	v_cmp_gt_u32_e32 vcc, s9, v33
	s_nop 1
	v_cndmask_b32_e32 v33, v189, v43, vcc
	v_cndmask_b32_e64 v36, v43, v33, s[64:65]
	v_add_u32_e32 v33, 56, v127
	v_cmp_gt_u32_e32 vcc, s9, v33
	v_max3_f32 v32, v32, v39, v36
	s_nop 0
	v_cndmask_b32_e32 v33, v189, v44, vcc
	v_cmp_gt_u32_e32 vcc, s9, v34
	v_cndmask_b32_e64 v33, v44, v33, s[64:65]
	s_nop 0
	v_cndmask_b32_e32 v34, v189, v45, vcc
	v_cndmask_b32_e64 v34, v45, v34, s[64:65]
	v_max3_f32 v40, v32, v33, v34
	v_add_u32_e32 v32, 58, v127
	v_cmp_gt_u32_e32 vcc, s9, v32
	s_nop 1
	v_cndmask_b32_e32 v32, v189, v46, vcc
	v_cndmask_b32_e64 v35, v46, v32, s[64:65]
	v_add_u32_e32 v32, 59, v127
	v_cmp_gt_u32_e32 vcc, s9, v32
	s_nop 1
	v_cndmask_b32_e32 v32, v189, v47, vcc
	v_cndmask_b32_e64 v32, v47, v32, s[64:65]
	v_max3_f32 v40, v40, v35, v32
